# P2 attention: waves of a workgroup start staggered by one key-tile step each (higher q-block first) so the 8 waves touch the same K/V tiles at the same time
# speedup vs baseline: 1.0018x; 1.0018x over previous
; __device__ __forceinline__ void sb_attn_unit(const bf16_t* __restrict__ Q, const bf16_t* __restrict__ Kb, const bf16_t* __restrict__ VT, bf16_t* __restrict__ MIX, int b, int h, int qb, int lane) {
;     const int q = lane & 31, hi = lane >> 5, q0 = qb * 32;
;     const size_t rowbase = (size_t)b * SEQ;
;     bf16x8 qf[4];
;     const size_t hb = (size_t)(b * 8 + h) * 8192;
;     { const bf16_t* qp = Q + (hb + q0 + q) * 64 + 8 * hi;
; #pragma unroll
;       for (int d0 = 0; d0 < 4; ++d0) qf[d0] = *(const bf16x8*)(qp + 16 * d0); }
;     const bf16_t* kp = Kb + hb * 64 + lane * 8;
;     const bf16_t* vp = VT + hb * 64 + lane * 8;
;     f32x16 o0, o1;
; #pragma unroll
;     for (int r = 0; r < 16; ++r) { o0[r] = 0.f; o1[r] = 0.f; }
;     float c = 0.f;
;     bf16x8 kf[4], vf[4], kn[4], vn[4];
; #pragma unroll
;     for (int i = 0; i < 4; ++i) { kf[i] = *(const bf16x8*)(kp + (size_t)q0 * 64 + 512 * i); vf[i] = *(const bf16x8*)(vp + (size_t)q0 * 64 + 512 * i); }
;     int kvn = q0 >= 32 ? q0 - 32 : 0;
; #pragma unroll
;     for (int i = 0; i < 4; ++i) { kn[i] = *(const bf16x8*)(kp + (size_t)kvn * 64 + 512 * i); vn[i] = *(const bf16x8*)(vp + (size_t)kvn * 64 + 512 * i); }
;     sb_tile<true>(kf, vf, qf, o0, o1, c, q - 16 * hi, hi);
; __global__ void __launch_bounds__(512, 2) hybrid_fwd(Args args) {
;     ...
;         for (int uidx = gw; uidx < NB * 8 * 256; uidx += NGW) {
;             const int qb = uidx & 255, bh = uidx >> 8;
;             sb_attn_unit(Qb, Kb, VT, MIX, bh >> 3, bh & 7, qb, lane);
.LBB0_349:
	s_cmp_lt_i32 s82, 3
	s_cselect_b64 s[8:9], -1, 0
	s_and_b64 s[6:7], s[8:9], s[6:7]
	s_andn2_b64 vcc, exec, s[6:7]
	s_cbranch_vccnz .LBB0_357
	v_mov_b32_e32 v0, v220
	s_lshl_b32 s6, s2, 3
	s_waitcnt lgkmcnt(0)
	v_readfirstlane_b32 s3, v0
	s_ashr_i32 s3, s3, 6
	s_sub_i32 s8, 7, s3
.Lp2_stag:
	s_cmp_lt_i32 s8, 1
	s_cbranch_scc1 .Lp2_stag_done
	s_sleep 80
	s_sub_i32 s8, s8, 1
	s_branch .Lp2_stag
.Lp2_stag_done:
	s_add_i32 s3, s3, s6
	s_cmpk_gt_i32 s3, 0x1fff
	s_cbranch_scc1 .LBB0_357
	s_load_dword s6, s[0:1], 0xb0
	v_bfe_u32 v3, v0, 5, 1
	v_mov_b32_e32 v79, 0
	v_lshlrev_b32_e32 v78, 4, v3
	v_and_b32_e32 v2, 63, v0
	v_and_b32_e32 v76, 31, v0
	s_waitcnt lgkmcnt(0)
	s_lshl_b32 s58, s6, 3
	v_lshl_add_u64 v[0:1], s[80:81], 0, v[78:79]
	s_mov_b64 s[6:7], 0x8200000
	v_lshl_add_u64 v[80:81], v[0:1], 0, s[6:7]
	v_lshlrev_b32_e32 v0, 4, v2
	v_mov_b32_e32 v1, v79
	v_lshl_add_u64 v[0:1], s[80:81], 0, v[0:1]
	s_mov_b64 s[6:7], 0xa200000
	v_lshl_add_u64 v[82:83], v[0:1], 0, s[6:7]
	s_mov_b64 s[6:7], 0xc200000
	v_lshl_add_u64 v[84:85], v[0:1], 0, s[6:7]
	v_sub_u32_e32 v0, v76, v78
	v_cmp_lt_i32_e64 s[6:7], 15, v0
	v_cmp_lt_i32_e64 s[8:9], 14, v0
	v_cmp_lt_i32_e64 s[10:11], 13, v0
	v_cmp_lt_i32_e64 s[12:13], 12, v0
	v_cmp_lt_i32_e64 s[14:15], 11, v0
	v_cmp_lt_i32_e64 s[16:17], 10, v0
	v_cmp_lt_i32_e64 s[18:19], 9, v0
	v_cmp_lt_i32_e64 s[20:21], 8, v0
	v_cmp_lt_i32_e64 s[22:23], 7, v0
	v_cmp_lt_i32_e64 s[24:25], 6, v0
	v_cmp_lt_i32_e64 s[26:27], 5, v0
	v_cmp_lt_i32_e64 s[28:29], 4, v0
	v_cmp_lt_i32_e64 s[30:31], 3, v0
	v_cmp_lt_i32_e64 s[34:35], 2, v0
	v_cmp_lt_i32_e64 s[36:37], 1, v0
	v_cmp_lt_i32_e64 s[38:39], 0, v0
	v_mbcnt_lo_u32_b32 v0, -1, 0
	v_mbcnt_hi_u32_b32 v0, -1, v0
	v_and_b32_e32 v4, 64, v0
	v_xor_b32_e32 v1, 32, v0
	v_add_u32_e32 v4, 64, v4
	v_cmp_lt_i32_e32 vcc, v1, v4
	s_add_u32 s42, s80, 0x14200000
	s_addc_u32 s43, s81, 0
	v_cndmask_b32_e32 v0, v0, v1, vcc
	v_lshlrev_b32_e32 v77, 2, v0
	v_lshlrev_b32_e32 v0, 2, v3
	s_mov_b32 s51, 0
	v_cmp_gt_u32_e64 s[40:41], 32, v2
	s_mov_b32 s59, 0xc316199a
	v_lshlrev_b32_e32 v78, 1, v0
	s_branch .LBB0_353
